# P10 EpiFinal residual-load hoist, temp SGPR pair s[14:15] instead of s[98:99]
# baseline (speedup 1.0000x reference)
.LBB0_958:
	s_lshl_b32 s52, s57, 8
	v_add_u32_e32 v168, s52, v179
	v_lshl_or_b32 v170, s12, 8, v181
	v_ashrrev_i32_e32 v171, 31, v170
	v_ashrrev_i32_e32 v169, 31, v168
	v_lshl_add_u64 v[128:129], v[170:171], 1, s[96:97]
	v_lshlrev_b64 v[130:131], 11, v[168:169]
	v_lshl_add_u64 v[172:173], v[128:129], 0, v[130:131]
	v_or_b32_e32 v130, 16, v168
	v_ashrrev_i32_e32 v131, 31, v130
	v_lshlrev_b64 v[130:131], 11, v[130:131]
	v_mov_b32_e32 v174, v214
	v_lshl_add_u64 v[130:131], v[128:129], 0, v[130:131]
	global_load_dwordx4 v[202:205], v[172:173], off
	global_load_dwordx4 v[206:209], v[172:173], off offset:256
	global_load_dwordx4 v[148:151], v[130:131], off
	global_load_dwordx4 v[144:147], v[130:131], off offset:256
	v_or_b32_e32 v130, 32, v168
	v_ashrrev_i32_e32 v131, 31, v130
	v_lshlrev_b64 v[130:131], 11, v[130:131]
	v_lshl_add_u64 v[130:131], v[128:129], 0, v[130:131]
	global_load_dwordx4 v[140:143], v[130:131], off
	global_load_dwordx4 v[136:139], v[130:131], off offset:256
	v_or_b32_e32 v130, 48, v168
	v_ashrrev_i32_e32 v131, 31, v130
	v_lshlrev_b64 v[130:131], 11, v[130:131]
	v_lshl_add_u64 v[128:129], v[128:129], 0, v[130:131]
	global_load_dwordx4 v[132:135], v[128:129], off
	s_nop 0
	global_load_dwordx4 v[128:131], v[128:129], off offset:256
	s_mov_b64 s[14:15], 0x40000
	v_lshl_add_u64 v[252:253], v[172:173], 0, s[14:15]
	global_load_dwordx4 v[216:219], v[252:253], off
	global_load_dwordx4 v[220:223], v[252:253], off offset:256
	s_mov_b64 s[14:15], 0x8000
	v_lshl_add_u64 v[252:253], v[252:253], 0, s[14:15]
	global_load_dwordx4 v[224:227], v[252:253], off
	global_load_dwordx4 v[228:231], v[252:253], off offset:256
	v_lshl_add_u64 v[252:253], v[252:253], 0, s[14:15]
	global_load_dwordx4 v[232:235], v[252:253], off
	global_load_dwordx4 v[244:247], v[252:253], off offset:256
	v_lshl_add_u64 v[252:253], v[252:253], 0, s[14:15]
	global_load_dwordx4 v[248:251], v[252:253], off
	v_and_b32_e32 v176, 64, v215
	v_xor_b32_e32 v175, 16, v215
	v_add_u32_e32 v176, 64, v176
	v_cmp_lt_i32_e32 vcc, v175, v176
	v_xor_b32_e32 v177, 32, v215
	s_nop 0
	v_cndmask_b32_e32 v175, v215, v175, vcc
	v_cmp_lt_i32_e32 vcc, v177, v176
	v_lshlrev_b32_e32 v175, 2, v175
	s_nop 0
	v_cndmask_b32_e32 v176, v215, v177, vcc
	v_lshlrev_b32_e32 v176, 2, v176
	s_waitcnt vmcnt(7)
	v_lshlrev_b32_e32 v210, 16, v202
	v_and_b32_e32 v211, 0xffff0000, v202
	v_lshlrev_b32_e32 v202, 16, v203
	v_and_b32_e32 v203, 0xffff0000, v203
	v_pk_add_f32 v[126:127], v[126:127], v[202:203]
	v_pk_add_f32 v[124:125], v[124:125], v[210:211]
	v_lshlrev_b32_e32 v212, 16, v204
	v_and_b32_e32 v213, 0xffff0000, v204
	v_mul_f32_e32 v177, v125, v125
	v_mul_f32_e32 v202, v127, v127
	v_pk_add_f32 v[120:121], v[120:121], v[212:213]
	v_fmac_f32_e32 v177, v124, v124
	v_fmac_f32_e32 v202, v126, v126
	v_lshlrev_b32_e32 v204, 16, v205
	v_and_b32_e32 v205, 0xffff0000, v205
	v_add_f32_e32 v177, v177, v202
	v_mul_f32_e32 v202, v121, v121
	v_pk_add_f32 v[122:123], v[122:123], v[204:205]
	v_fmac_f32_e32 v202, v120, v120
	v_add_f32_e32 v177, v202, v177
	v_mul_f32_e32 v202, v123, v123
	v_fmac_f32_e32 v202, v122, v122
	v_add_f32_e32 v177, v202, v177
	v_lshlrev_b32_e32 v202, 16, v206
	v_and_b32_e32 v203, 0xffff0000, v206
	v_lshlrev_b32_e32 v204, 16, v207
	v_and_b32_e32 v205, 0xffff0000, v207
	v_pk_add_f32 v[118:119], v[118:119], v[204:205]
	v_pk_add_f32 v[116:117], v[116:117], v[202:203]
	v_lshlrev_b32_e32 v206, 16, v208
	v_and_b32_e32 v207, 0xffff0000, v208
	v_mul_f32_e32 v202, v117, v117
	v_mul_f32_e32 v203, v119, v119
	v_pk_add_f32 v[112:113], v[112:113], v[206:207]
	v_fmac_f32_e32 v202, v116, v116
	v_fmac_f32_e32 v203, v118, v118
	v_lshlrev_b32_e32 v208, 16, v209
	v_and_b32_e32 v209, 0xffff0000, v209
	v_add_f32_e32 v202, v202, v203
	v_mul_f32_e32 v203, v113, v113
	v_pk_add_f32 v[114:115], v[114:115], v[208:209]
	v_fmac_f32_e32 v203, v112, v112
	v_add_f32_e32 v202, v203, v202
	v_mul_f32_e32 v203, v115, v115
	v_fmac_f32_e32 v203, v114, v114
	v_add_f32_e32 v202, v203, v202
	v_add_f32_e32 v177, v177, v202
	ds_bpermute_b32 v202, v175, v177
	s_waitcnt lgkmcnt(0)
	v_add_f32_e32 v177, v177, v202
	ds_bpermute_b32 v202, v176, v177
	s_and_saveexec_b64 s[14:15], s[0:1]
	s_cbranch_execz .LBB0_960
	s_waitcnt lgkmcnt(0)
	v_add_f32_e32 v177, v177, v202
	ds_write_b32 v201, v177
